# v69 = v68 + packed f32 ops within 8 slots of an MFMA split into scalar pairs in own / LRU / sb (bit-identical)
# baseline (speedup 1.0000x reference)
.LBB0_226:
	s_or_b64 exec, exec, s[12:13]
	s_lshl_b32 s0, s5, 8
	s_and_b32 s0, s0, 0xf00
	ds_read_b128 v[64:67], v221
	ds_read_b128 v[68:71], v221 offset:64
	ds_read_b128 v[76:79], v221 offset:2304
	ds_read_b128 v[80:83], v221 offset:2368
	v_or_b32_e32 v101, v168, v122
	v_or_b32_e32 v116, 3, v101
	v_cmp_lt_u32_e64 s[28:29], v116, v100
	v_or_b32_e32 v102, 16, v100
	v_cmp_lt_u32_e64 s[12:13], v101, v102
	v_cmp_lt_u32_e64 s[14:15], v116, v102
	s_waitcnt lgkmcnt(3)
	v_mfma_f32_16x16x32_bf16 v[72:75], v[64:67], v[48:51], 0
	s_waitcnt lgkmcnt(1)
	v_mfma_f32_16x16x32_bf16 v[84:87], v[76:79], v[48:51], 0
	v_mfma_f32_16x16x32_bf16 v[88:91], v[76:79], v[52:55], 0
	v_mfma_f32_16x16x32_bf16 v[72:75], v[68:71], v[56:59], v[72:75]
	v_mfma_f32_16x16x32_bf16 v[64:67], v[64:67], v[52:55], 0
	s_waitcnt lgkmcnt(0)
	v_mfma_f32_16x16x32_bf16 v[76:79], v[80:83], v[56:59], v[84:87]
	s_nop 4
	v_mul_f32_e64 v92, |v75|, s51
	v_mfma_f32_16x16x32_bf16 v[80:83], v[80:83], v[60:63], v[88:91]
	v_max_f32_e32 v87, v73, v73
	v_max_f32_e32 v113, 0, v87
	v_max_f32_e32 v84, v72, v72
	v_mul_f32_e64 v88, |v73|, s51
	v_mfma_f32_16x16x32_bf16 v[68:71], v[68:71], v[60:63], v[64:67]
	v_exp_f32_e32 v87, v88
	v_max_f32_e32 v104, v76, v76
	v_mul_f32_e64 v110, |v79|, s51
	v_max_f32_e32 v89, v74, v74
	v_add_f32_e32 v87, 1.0, v87
	s_nop 2
	v_max_f32_e32 v97, v70, v70
	v_mul_f32_e64 v90, |v74|, s51
	v_max_f32_e32 v91, v75, v75
	v_max_f32_e32 v93, v68, v68
	v_mul_f32_e64 v94, |v68|, s51
	v_mul_f32_e64 v96, |v69|, s51
	v_mul_f32_e64 v98, |v70|, s51
	v_mul_f32_e64 v107, |v77|, s51
	v_max_f32_e32 v111, 0, v84
	v_max_f32_e32 v84, 0, v97
	v_max_f32_e32 v97, 0, v104
	v_exp_f32_e32 v104, v110
	v_log_f32_e32 v87, v87
	v_mul_f32_e64 v105, |v76|, s51
	v_max_f32_e32 v114, 0, v89
	v_exp_f32_e32 v89, v90
	v_max_f32_e32 v115, 0, v91
	v_exp_f32_e32 v90, v92
	v_max_f32_e32 v92, 0, v93
	v_exp_f32_e32 v91, v94
	v_exp_f32_e32 v93, v96
	v_exp_f32_e32 v94, v98
	v_exp_f32_e32 v98, v107
	v_exp_f32_e32 v96, v105
	v_fmac_f32_e32 v113, 0x3f317218, v87
	v_add_f32_e32 v87, 1.0, v104
	v_max_f32_e32 v95, v69, v69
	v_mul_f32_e64 v103, |v71|, s51
	v_max_f32_e32 v106, v77, v77
	v_add_f32_e32 v93, 1.0, v93
	v_add_f32_e32 v107, 1.0, v98
	v_log_f32_e32 v87, v87
	v_or_b32_e32 v85, 16, v101
	v_max_f32_e32 v88, 0, v95
	v_exp_f32_e32 v95, v103
	v_max_f32_e32 v103, 0, v106
	v_add_f32_e32 v106, 1.0, v96
	v_log_f32_e32 v96, v93
	v_log_f32_e32 v93, v107
	v_cmp_lt_u32_e32 vcc, v85, v100
	v_max_f32_e32 v85, v79, v79
	v_mul_f32_e64 v86, |v72|, s51
	v_max_f32_e32 v99, v71, v71
	v_mul_f32_e64 v109, |v78|, s51
	v_max_f32_e32 v104, 0, v85
	v_mul_f32_e64 v85, |v80|, s51
	v_exp_f32_e32 v112, v86
	v_max_f32_e32 v86, 0, v99
	v_exp_f32_e32 v99, v109
	v_exp_f32_e32 v85, v85
	v_fmac_f32_e32 v104, 0x3f317218, v87
	v_max_f32_e32 v87, v80, v80
	v_add_f32_e32 v89, 1.0, v89
	v_fmac_f32_e32 v103, 0x3f317218, v93
	v_max_f32_e32 v93, 0, v87
	v_mul_f32_e64 v87, |v81|, s51
	v_add_f32_e32 v91, 1.0, v91
	v_log_f32_e32 v89, v89
	v_exp_f32_e32 v87, v87
	v_log_f32_e32 v98, v91
	v_log_f32_e32 v91, v106
	v_add_f32_e32 v90, 1.0, v90
	v_add_f32_e32 v94, 1.0, v94
	v_add_f32_e32 v95, 1.0, v95
	v_add_f32_e32 v99, 1.0, v99
	v_add_f32_e32 v85, 1.0, v85
	v_log_f32_e32 v109, v90
	v_log_f32_e32 v90, v94
	v_log_f32_e32 v94, v95
	v_log_f32_e32 v95, v99
	v_log_f32_e32 v99, v85
	v_max_f32_e32 v85, v81, v81
	v_fmac_f32_e32 v114, 0x3f317218, v89
	v_max_f32_e32 v89, 0, v85
	v_add_f32_e32 v85, 1.0, v87
	v_mul_f32_e64 v87, |v82|, s51
	v_fmac_f32_e32 v97, 0x3f317218, v91
	v_exp_f32_e32 v91, v87
	v_cndmask_b32_e64 v106, 0, -v97, vcc
	v_log_f32_e32 v97, v85
	v_max_f32_e32 v85, v82, v82
	v_add_f32_e32 v105, 1.0, v112
	v_max_f32_e32 v87, 0, v85
	v_add_f32_e32 v85, 1.0, v91
	v_mul_f32_e64 v91, |v83|, s51
	v_log_f32_e32 v105, v105
	v_exp_f32_e32 v91, v91
	v_max_f32_e32 v108, v78, v78
	v_fmac_f32_e32 v115, 0x3f317218, v109
	v_or_b32_e32 v109, 1, v101
	v_or_b32_e32 v112, 2, v101
	v_fmac_f32_e32 v111, 0x3f317218, v105
	v_max_f32_e32 v107, 0, v108
	v_add_f32_e32 v91, 1.0, v91
	v_cmp_lt_u32_e64 s[36:37], v109, v100
	v_cmp_lt_u32_e64 s[26:27], v112, v100
	v_cndmask_b32_e64 v105, 0, -v111, s[10:11]
	v_fmac_f32_e32 v107, 0x3f317218, v95
	v_log_f32_e32 v95, v85
	v_log_f32_e32 v91, v91
	v_cndmask_b32_e64 v110, 0, -v113, s[36:37]
	v_or_b32_e32 v111, 19, v101
	v_cndmask_b32_e64 v113, 0, -v114, s[26:27]
	v_or_b32_e32 v114, 18, v101
	v_or_b32_e32 v108, 17, v101
	v_cmp_lt_u32_e64 s[30:31], v114, v100
	v_cmp_lt_u32_e64 s[34:35], v111, v100
	v_max_f32_e32 v85, v83, v83
	v_cndmask_b32_e64 v115, 0, -v115, s[28:29]
	v_cmp_lt_u32_e64 s[38:39], v108, v100
	v_cndmask_b32_e64 v107, 0, -v107, s[30:31]
	v_cndmask_b32_e64 v100, 0, -v104, s[34:35]
	v_max_f32_e32 v85, 0, v85
	v_cndmask_b32_e64 v103, 0, -v103, s[38:39]
	v_pk_fma_f32 v[92:93], v[98:99], s[62:63], v[92:93] op_sel_hi:[1,0,1]
	v_cmp_lt_u32_e64 s[18:19], v108, v102
	v_cmp_lt_u32_e64 s[20:21], v109, v102
	v_cmp_lt_u32_e64 s[16:17], v114, v102
	v_cmp_lt_u32_e64 s[22:23], v111, v102
	v_cmp_lt_u32_e64 s[24:25], v112, v102
	v_add_f32_e32 v98, v115, v113
	v_add_f32_e32 v102, v100, v107
	v_pk_fma_f32 v[86:87], v[94:95], s[62:63], v[86:87] op_sel_hi:[1,0,1]
	v_pk_fma_f32 v[84:85], v[90:91], s[62:63], v[84:85] op_sel_hi:[1,0,1]
	v_add_f32_e32 v99, v110, v98
	v_add_f32_e32 v103, v103, v102
	v_pk_fma_f32 v[88:89], v[96:97], s[62:63], v[88:89] op_sel_hi:[1,0,1]
	v_cndmask_b32_e64 v87, 0, -v87, s[16:17]
	v_cndmask_b32_e64 v86, 0, -v86, s[14:15]
	v_cndmask_b32_e64 v85, 0, -v85, s[22:23]
	v_cndmask_b32_e64 v84, 0, -v84, s[24:25]
	v_add_f32_e32 v101, v105, v99
	v_add_f32_e32 v105, v106, v103
	v_cndmask_b32_e64 v89, 0, -v89, s[18:19]
	v_cndmask_b32_e64 v88, 0, -v88, s[20:21]
	v_pk_add_f32 v[90:91], v[84:85], v[86:87]
	v_mov_b32_e32 v84, v101
	v_mov_b32_e32 v87, v101
	v_mov_b32_e32 v94, v105
	v_mov_b32_e32 v95, v105
	v_cndmask_b32_e64 v93, 0, -v93, s[10:11]
	v_cndmask_b32_e64 v92, 0, -v92, s[12:13]
	v_pk_add_f32 v[88:89], v[88:89], v[90:91]
	v_permlane16_swap_b32_e32 v84, v87
	v_permlane16_swap_b32_e32 v94, v95
	v_pk_add_f32 v[92:93], v[92:93], v[88:89]
	v_cndmask_b32_e64 v84, v84, v87, s[8:9]
	v_cndmask_b32_e64 v94, v94, v95, s[8:9]
	v_add_f32_e32 v108, v101, v84
	v_mov_b32_e32 v84, v92
	v_mov_b32_e32 v87, v92
	v_add_f32_e32 v106, v105, v94
	v_mov_b32_e32 v94, v93
	v_mov_b32_e32 v95, v93
	v_permlane16_swap_b32_e32 v84, v87
	s_nop 0
	v_permlane16_swap_b32_e32 v94, v95
	v_cndmask_b32_e64 v95, v94, v95, s[8:9]
	v_cndmask_b32_e64 v94, v84, v87, s[8:9]
	v_mov_b32_e32 v84, v108
	v_mov_b32_e32 v87, v108
	v_mov_b32_e32 v96, v106
	v_mov_b32_e32 v97, v106
	v_pk_add_f32 v[94:95], v[92:93], v[94:95]
	v_permlane32_swap_b32_e32 v84, v87
	v_permlane32_swap_b32_e32 v96, v97
	v_cndmask_b32_e64 v109, v84, v87, s[6:7]
	v_mov_b32_e32 v84, v94
	v_mov_b32_e32 v87, v94
	v_cndmask_b32_e64 v107, v96, v97, s[6:7]
	v_mov_b32_e32 v96, v95
	v_mov_b32_e32 v97, v95
	v_permlane32_swap_b32_e32 v84, v87
	s_nop 0
	v_permlane32_swap_b32_e32 v96, v97
	v_add_f32_e32 v104, v106, v107
	v_cndmask_b32_e64 v97, v96, v97, s[6:7]
	v_cndmask_b32_e64 v96, v84, v87, s[6:7]
	v_sub_f32_e32 v84, v106, v105
	v_add_f32_e32 v87, 0, v104
	v_sub_f32_e32 v106, v108, v101
	v_fmac_f32_e32 v87, v208, v106
	v_fmac_f32_e32 v87, v209, v109
	v_add_f32_e32 v72, v72, v87
	v_add_f32_e32 v73, v73, v87
	v_add_f32_e32 v72, v101, v72
	v_add_f32_e32 v73, v99, v73
	v_mul_f32_e32 v72, 0x3fb8aa3b, v72
	v_mul_f32_e32 v73, 0x3fb8aa3b, v73
	v_exp_f32_e32 v72, v72
	v_exp_f32_e32 v73, v73
	v_fma_f32 v84, v208, v84, 0
	v_fmac_f32_e32 v84, v209, v107
	v_cndmask_b32_e64 v99, 0, v72, s[10:11]
	v_cndmask_b32_e64 v101, 0, v73, s[36:37]
	v_add_f32_e32 v72, v78, v84
	v_add_f32_e32 v73, v74, v87
	v_add_f32_e32 v72, v102, v72
	v_add_f32_e32 v73, v98, v73
	v_mul_f32_e32 v72, 0x3fb8aa3b, v72
	v_mul_f32_e32 v73, 0x3fb8aa3b, v73
	v_exp_f32_e32 v72, v72
	v_exp_f32_e32 v73, v73
	v_add_f32_e32 v74, v79, v84
	v_pk_add_f32 v[106:107], v[94:95], v[96:97]
	v_cndmask_b32_e64 v78, 0, v72, s[30:31]
	v_cndmask_b32_e64 v79, 0, v73, s[26:27]
	v_pk_add_f32 v[72:73], v[94:95], v[92:93] neg_lo:[0,1] neg_hi:[0,1]
	v_add_f32_e32 v76, v76, v84
	v_fma_f32 v73, v208, v73, 0
	v_add_f32_e32 v77, v77, v84
	v_fmac_f32_e32 v73, v209, v97
	v_add_f32_e32 v84, 0, v107
	v_fmac_f32_e32 v84, v208, v72
	v_add_f32_e32 v72, v80, v73
	v_add_f32_e32 v80, v81, v73
	v_add_f32_e32 v80, v89, v80
	v_mul_f32_e32 v80, 0x3fb8aa3b, v80
	v_exp_f32_e32 v80, v80
	v_fmac_f32_e32 v84, v209, v96
	ds_read2_b64 v[64:67], v222 offset0:32 offset1:36
	v_add_f32_e32 v75, v75, v87
	v_add_f32_e32 v68, v68, v84
	v_add_f32_e32 v69, v69, v84
	v_cndmask_b32_e64 v87, 0, v80, s[18:19]
	v_add_f32_e32 v80, v82, v73
	v_add_f32_e32 v70, v70, v84
	v_add_f32_e32 v73, v83, v73
	v_add_f32_e32 v71, v71, v84
	v_add_f32_e32 v76, v105, v76
	v_add_f32_e32 v77, v103, v77
	v_add_f32_e32 v74, v100, v74
	v_add_f32_e32 v75, v115, v75
	v_add_f32_e32 v72, v93, v72
	v_add_f32_e32 v68, v92, v68
	v_add_f32_e32 v69, v88, v69
	v_add_f32_e32 v80, v91, v80
	v_add_f32_e32 v70, v90, v70
	v_add_f32_e32 v73, v85, v73
	v_add_f32_e32 v71, v86, v71
	v_mul_f32_e32 v76, 0x3fb8aa3b, v76
	v_mul_f32_e32 v77, 0x3fb8aa3b, v77
	v_mul_f32_e32 v74, 0x3fb8aa3b, v74
	v_mul_f32_e32 v75, 0x3fb8aa3b, v75
	v_mul_f32_e32 v72, 0x3fb8aa3b, v72
	v_mul_f32_e32 v68, 0x3fb8aa3b, v68
	v_mul_f32_e32 v69, 0x3fb8aa3b, v69
	v_mul_f32_e32 v80, 0x3fb8aa3b, v80
	v_mul_f32_e32 v70, 0x3fb8aa3b, v70
	v_mul_f32_e32 v73, 0x3fb8aa3b, v73
	v_mul_f32_e32 v71, 0x3fb8aa3b, v71
	v_exp_f32_e32 v76, v76
	v_exp_f32_e32 v77, v77
	v_exp_f32_e32 v74, v74
	v_exp_f32_e32 v75, v75
	v_exp_f32_e32 v72, v72
	v_exp_f32_e32 v68, v68
	v_exp_f32_e32 v69, v69
	v_exp_f32_e32 v80, v80
	v_exp_f32_e32 v70, v70
	v_exp_f32_e32 v73, v73
	v_exp_f32_e32 v71, v71
	v_cndmask_b32_e32 v76, 0, v76, vcc
	v_cndmask_b32_e64 v77, 0, v77, s[38:39]
	v_cndmask_b32_e64 v74, 0, v74, s[34:35]
	v_cndmask_b32_e64 v75, 0, v75, s[28:29]
	v_cndmask_b32_e64 v72, 0, v72, s[10:11]
	v_cndmask_b32_e64 v68, 0, v68, s[12:13]
	v_cndmask_b32_e64 v69, 0, v69, s[20:21]
	v_cndmask_b32_e64 v84, 0, v80, s[16:17]
	v_cndmask_b32_e64 v70, 0, v70, s[24:25]
	v_cndmask_b32_e64 v73, 0, v73, s[22:23]
	v_cndmask_b32_e64 v71, 0, v71, s[14:15]
	v_cvt_pk_bf16_f32 v80, v99, v101
	v_cvt_pk_bf16_f32 v81, v79, v75
	v_cvt_pk_bf16_f32 v82, v76, v77
	v_cvt_pk_bf16_f32 v83, v78, v74
	v_cvt_pk_bf16_f32 v96, v68, v69
	v_cvt_pk_bf16_f32 v97, v70, v71
	v_cvt_pk_bf16_f32 v98, v72, v87
	v_cvt_pk_bf16_f32 v99, v84, v73
	s_waitcnt lgkmcnt(0)
	v_mfma_f32_16x16x32_bf16 v[92:95], v[64:67], v[80:83], 0
	ds_read2_b64 v[100:103], v212 offset1:4
	s_add_i32 s14, s0, 0xffffff80
	s_cmp_eq_u32 s0, 0
	v_mfma_f32_16x16x32_bf16 v[76:79], v[64:67], v[96:99], 0
	ds_read2_b64 v[64:67], v210 offset1:4
	s_cselect_b64 s[12:13], -1, 0
	v_mov_b32_e32 v105, v107
	s_waitcnt lgkmcnt(0)
	v_mfma_f32_16x16x32_bf16 v[88:91], v[64:67], v[80:83], 0
	s_and_b64 s[0:1], s[12:13], exec
	s_cselect_b32 s22, 0, s14
	v_mfma_f32_16x16x32_bf16 v[72:75], v[64:67], v[96:99], 0
	ds_read2_b64 v[64:67], v211 offset1:4
	s_waitcnt lgkmcnt(0)
	v_mfma_f32_16x16x32_bf16 v[84:87], v[64:67], v[80:83], 0
	v_mfma_f32_16x16x32_bf16 v[68:71], v[64:67], v[96:99], 0
	v_add_f32_e32 v64, v108, v109
	v_mov_b32_e32 v65, v106
	v_add_f32_e32 v104, v64, v104
	v_add_f32_e32 v105, v65, v105
	v_mfma_f32_16x16x32_bf16 v[80:83], v[100:103], v[80:83], 0
	v_cmp_gt_f32_e32 vcc, s63, v104
	v_cmp_gt_f32_e64 s[0:1], s63, v105
	s_and_b64 s[0:1], vcc, s[0:1]
	v_mfma_f32_16x16x32_bf16 v[64:67], v[100:103], v[96:99], 0
	v_cndmask_b32_e64 v96, 0, 1, s[0:1]
	v_cmp_ne_u32_e32 vcc, 0, v96
	v_add_f32_e32 v170, 0, v104
	v_add_f32_e32 v171, 0, v105
	s_cmp_eq_u64 vcc, exec
	s_mov_b64 s[0:1], -1
	s_cbranch_scc1 .LBB0_232
	v_cmp_lt_i32_e32 vcc, s22, v168
	s_mov_b64 s[0:1], 0
	s_and_saveexec_b64 s[14:15], vcc
	s_cbranch_execz .LBB0_231
	s_and_b32 s0, s33, 0xf00
	v_add_u32_e32 v112, s0, v213
	s_mov_b64 s[16:17], 0
	v_mov_b32_e32 v113, v214
	v_mov_b32_e32 v114, v125

.Lown_wd2:
	s_waitcnt lgkmcnt(1)
	v_mfma_f32_16x16x32_bf16 v[204:207], v[168:171], v[20:23], 0
	v_mfma_f32_16x16x32_bf16 v[168:171], v[168:171], v[28:31], 0
	s_waitcnt lgkmcnt(0)
	v_mfma_f32_16x16x32_bf16 v[204:207], v[200:203], v[24:27], v[204:207]
	v_mfma_f32_16x16x32_bf16 v[168:171], v[200:203], v[32:35], v[168:171]
	ds_read_b128 v[200:203], v67 offset:4608
	ds_read_b128 v[208:211], v67 offset:4672
	ds_read_b128 v[216:219], v67 offset:6912
	ds_read_b128 v[220:223], v67 offset:6976
	v_mfma_f32_16x16x32_bf16 v[164:167], v[156:159], v[20:23], 0
	v_mfma_f32_16x16x32_bf16 v[156:159], v[156:159], v[28:31], 0
	v_mfma_f32_16x16x32_bf16 v[164:167], v[160:163], v[24:27], v[164:167]
	s_waitcnt lgkmcnt(3)
	v_mfma_f32_16x16x32_bf16 v[212:215], v[200:203], v[20:23], 0
	v_mfma_f32_16x16x32_bf16 v[200:203], v[200:203], v[28:31], 0
	s_nop 4
	v_max3_f32 v73, v164, s5, v165
	v_max3_f32 v73, v73, v166, v167
	v_max3_f32 v73, v73, v204, v205
	s_waitcnt lgkmcnt(1)
	v_mfma_f32_16x16x32_bf16 v[224:227], v[216:219], v[20:23], 0
	v_max3_f32 v73, v73, v206, v207
	v_mfma_f32_16x16x32_bf16 v[158:161], v[160:163], v[32:35], v[156:159]
	v_mfma_f32_16x16x32_bf16 v[212:215], v[208:211], v[24:27], v[212:215]
	s_waitcnt lgkmcnt(0)
	v_mfma_f32_16x16x32_bf16 v[224:227], v[220:223], v[24:27], v[224:227]
	s_nop 4
	v_max3_f32 v75, v158, s5, v159
	v_max3_f32 v73, v73, v212, v213
	v_max3_f32 v73, v73, v214, v215
	v_mfma_f32_16x16x32_bf16 v[200:203], v[208:211], v[32:35], v[200:203]
	v_max3_f32 v75, v75, v160, v161
	v_max3_f32 v73, v73, v224, v225
	v_max3_f32 v75, v75, v168, v169
	v_mfma_f32_16x16x32_bf16 v[208:211], v[216:219], v[28:31], 0
	v_max3_f32 v73, v73, v226, v227
	v_max3_f32 v75, v75, v170, v171
	s_nop 1
	v_max3_f32 v75, v75, v200, v201
	v_mfma_f32_16x16x32_bf16 v[208:211], v[220:223], v[32:35], v[208:211]
	v_mov_b32_e32 v95, v73
	v_max3_f32 v75, v75, v202, v203
	s_nop 0
	v_permlane16_swap_b32_e32 v95, v73
	s_nop 3
	v_max3_f32 v75, v75, v208, v209
	v_max3_f32 v75, v75, v210, v211
	v_max_f32_e32 v73, v73, v95
	v_mov_b32_e32 v95, v75
	s_nop 1
	v_permlane16_swap_b32_e32 v95, v75
	v_max_f32_e32 v75, v75, v95
	v_mov_b32_e32 v95, v73
	v_mov_b32_e32 v99, v75
	s_nop 1
	v_permlane32_swap_b32_e32 v95, v73
	v_permlane32_swap_b32_e32 v99, v75
	v_max3_f32 v75, v69, v75, v99
	v_max3_f32 v73, v71, v73, v95
	v_sub_f32_e32 v69, v69, v75
	v_exp_f32_e32 v157, v69
	v_sub_f32_e32 v69, v164, v73
	v_exp_f32_e32 v172, v69
	v_sub_f32_e32 v69, v158, v75
	v_exp_f32_e32 v173, v69
	v_sub_f32_e32 v69, v165, v73
	v_exp_f32_e32 v178, v69
	v_sub_f32_e32 v69, v159, v75
	v_exp_f32_e32 v179, v69
	v_sub_f32_e32 v69, v166, v73
	v_exp_f32_e32 v216, v69
	v_sub_f32_e32 v69, v160, v75
	v_exp_f32_e32 v217, v69
	v_sub_f32_e32 v69, v167, v73
	v_exp_f32_e32 v218, v69
	v_sub_f32_e32 v69, v161, v75
	v_exp_f32_e32 v219, v69
	v_sub_f32_e32 v69, v204, v73
	v_exp_f32_e32 v220, v69
	v_sub_f32_e32 v69, v168, v75
	v_exp_f32_e32 v221, v69
	v_sub_f32_e32 v69, v205, v73
	v_exp_f32_e32 v204, v69
	v_sub_f32_e32 v69, v169, v75
	v_exp_f32_e32 v205, v69
	v_sub_f32_e32 v69, v206, v73
	v_exp_f32_e32 v222, v69
	v_sub_f32_e32 v69, v170, v75
	v_exp_f32_e32 v223, v69
	v_sub_f32_e32 v69, v207, v73
	v_exp_f32_e32 v206, v69
	v_sub_f32_e32 v69, v171, v75
	v_exp_f32_e32 v207, v69
	v_sub_f32_e32 v69, v212, v73
	v_exp_f32_e32 v228, v69
	v_sub_f32_e32 v69, v200, v75
	v_exp_f32_e32 v229, v69
	v_sub_f32_e32 v69, v213, v73
	v_exp_f32_e32 v212, v69
	v_sub_f32_e32 v69, v201, v75
	v_exp_f32_e32 v213, v69
	v_sub_f32_e32 v69, v214, v73
	v_exp_f32_e32 v230, v69
	v_sub_f32_e32 v69, v202, v75
	v_pk_add_f32 v[158:159], v[172:173], 0 op_sel_hi:[1,0]
	v_exp_f32_e32 v231, v69
	v_sub_f32_e32 v69, v215, v73
	v_pk_add_f32 v[158:159], v[178:179], v[158:159]
	v_exp_f32_e32 v214, v69
	v_sub_f32_e32 v69, v203, v75
	v_pk_add_f32 v[158:159], v[216:217], v[158:159]
	v_exp_f32_e32 v215, v69
	v_sub_f32_e32 v69, v224, v73
	ds_read2_b64 v[166:169], v65 offset1:4
	v_pk_add_f32 v[158:159], v[218:219], v[158:159]
	v_exp_f32_e32 v232, v69
	v_sub_f32_e32 v69, v208, v75
	v_pk_add_f32 v[158:159], v[220:221], v[158:159]
	v_exp_f32_e32 v233, v69
	v_sub_f32_e32 v69, v225, v73
	v_sub_f32_e32 v71, v71, v73
	v_pk_add_f32 v[158:159], v[204:205], v[158:159]
	v_exp_f32_e32 v208, v69
	v_sub_f32_e32 v69, v209, v75
	v_exp_f32_e32 v156, v71
	v_pk_add_f32 v[158:159], v[222:223], v[158:159]
	v_exp_f32_e32 v209, v69
	v_sub_f32_e32 v69, v226, v73
	ds_read2_b64 v[200:203], v65 offset0:8 offset1:12
	v_pk_add_f32 v[170:171], v[206:207], v[158:159]
	v_exp_f32_e32 v224, v69
	v_sub_f32_e32 v69, v210, v75
	v_exp_f32_e32 v225, v69
	v_sub_f32_e32 v69, v227, v73
	v_pk_add_f32 v[170:171], v[228:229], v[170:171]
	v_exp_f32_e32 v210, v69
	v_sub_f32_e32 v69, v211, v75
	v_cvt_pk_bf16_f32 v158, v172, v178
	v_pk_add_f32 v[170:171], v[212:213], v[170:171]
	v_mov_b32_e32 v178, v157
	v_exp_f32_e32 v211, v69
	v_pk_mul_f32 v[46:47], v[46:47], v[156:157] op_sel_hi:[1,0]
	v_pk_mul_f32 v[44:45], v[44:45], v[156:157] op_sel_hi:[1,0]
	v_cvt_pk_bf16_f32 v159, v216, v218
	v_cvt_pk_bf16_f32 v160, v220, v204
	v_cvt_pk_bf16_f32 v161, v222, v206
	v_pk_add_f32 v[226:227], v[230:231], v[170:171]
	v_pk_mul_f32 v[14:15], v[14:15], v[178:179] op_sel_hi:[1,0]
	v_pk_mul_f32 v[12:13], v[12:13], v[178:179] op_sel_hi:[1,0]
	v_cvt_pk_bf16_f32 v170, v173, v179
	v_cvt_pk_bf16_f32 v171, v217, v219
	v_cvt_pk_bf16_f32 v172, v221, v205
	v_cvt_pk_bf16_f32 v173, v223, v207
	s_waitcnt lgkmcnt(1)
	v_mfma_f32_16x16x32_bf16 v[44:47], v[166:169], v[158:161], v[44:47]
	v_add_u32_e32 v69, 0x2000, v65
	ds_read2_b64 v[204:207], v69 offset0:32 offset1:36
	v_cvt_pk_bf16_f32 v162, v228, v212
	v_mfma_f32_16x16x32_bf16 v[12:15], v[166:169], v[170:173], v[12:15]
	v_cvt_pk_bf16_f32 v163, v230, v214
	v_cvt_pk_bf16_f32 v164, v232, v208
	v_cvt_pk_bf16_f32 v165, v224, v210
	v_cvt_pk_bf16_f32 v166, v229, v213
	v_cvt_pk_bf16_f32 v167, v231, v215
	v_cvt_pk_bf16_f32 v168, v233, v209
	v_cvt_pk_bf16_f32 v169, v225, v211
	s_waitcnt lgkmcnt(1)
	v_mfma_f32_16x16x32_bf16 v[44:47], v[200:203], v[162:165], v[44:47]
	v_mul_f32_e64 v42, v42, v156
	v_mul_f32_e64 v43, v43, v156
	v_mul_f32_e32 v40, v40, v156
	v_mul_f32_e32 v41, v41, v156
	v_mul_f32_e32 v10, v10, v178
	v_mul_f32_e32 v11, v11, v178
	v_mfma_f32_16x16x32_bf16 v[12:15], v[200:203], v[166:169], v[12:15]
	v_add_f32_e64 v200, v214, v226
	v_add_f32_e64 v201, v215, v227
	v_mul_f32_e32 v8, v8, v178
	v_mul_f32_e32 v9, v9, v178
	v_add_f32_e32 v212, v232, v200
	v_add_f32_e32 v213, v233, v201
	ds_read2_b64 v[200:203], v69 offset0:40 offset1:44
	v_add_u32_e32 v69, 0x4000, v65
	s_waitcnt lgkmcnt(1)
	v_mfma_f32_16x16x32_bf16 v[40:43], v[204:207], v[158:161], v[40:43]
	v_add_f32_e64 v208, v208, v212
	v_add_f32_e64 v209, v209, v213
	v_mul_f32_e32 v38, v38, v156
	v_mul_f32_e32 v39, v39, v156
	v_add_f32_e32 v208, v224, v208
	v_add_f32_e32 v209, v225, v209
	v_mfma_f32_16x16x32_bf16 v[8:11], v[204:207], v[170:173], v[8:11]
	ds_read2_b64 v[204:207], v69 offset0:64 offset1:68
	v_add_f32_e32 v208, v210, v208
	v_add_f32_e32 v209, v211, v209
	v_mul_f32_e32 v36, v36, v156
	v_mul_f32_e32 v37, v37, v156
	s_waitcnt lgkmcnt(1)
	v_mfma_f32_16x16x32_bf16 v[40:43], v[200:203], v[162:165], v[40:43]
	v_mov_b32_e32 v99, v209
	v_mul_f32_e32 v6, v6, v178
	v_mul_f32_e32 v7, v7, v178
	v_mul_f32_e32 v4, v4, v178
	v_mul_f32_e32 v5, v5, v178
	v_mfma_f32_16x16x32_bf16 v[8:11], v[200:203], v[166:169], v[8:11]
	ds_read2_b64 v[200:203], v69 offset0:72 offset1:76
	v_mov_b32_e32 v69, v209
	s_nop 1
	v_permlane16_swap_b32_e32 v99, v69
	v_cndmask_b32_e64 v211, v99, v69, s[8:9]
	v_add_u32_e32 v69, 0x6000, v65
	s_waitcnt lgkmcnt(1)
	v_mfma_f32_16x16x32_bf16 v[36:39], v[204:207], v[158:161], v[36:39]
	v_mul_f32_e64 v18, v18, v156
	v_mul_f32_e64 v19, v19, v156
	v_mul_f32_e32 v16, v16, v156
	v_mul_f32_e32 v17, v17, v156
	v_mov_b32_e32 v71, v208
	v_mfma_f32_16x16x32_bf16 v[4:7], v[204:207], v[170:173], v[4:7]
	ds_read2_b64 v[204:207], v69 offset0:96 offset1:100
	v_mov_b32_e32 v95, v208
	v_mul_f32_e32 v2, v2, v178
	v_mul_f32_e32 v3, v3, v178
	s_waitcnt lgkmcnt(1)
	v_mfma_f32_16x16x32_bf16 v[36:39], v[200:203], v[162:165], v[36:39]
	v_mul_f32_e64 v0, v0, v178
	v_mul_f32_e64 v1, v1, v178
	v_permlane16_swap_b32_e32 v71, v95
	v_mfma_f32_16x16x32_bf16 v[4:7], v[200:203], v[166:169], v[4:7]
	ds_read2_b64 v[200:203], v69 offset0:104 offset1:108
	v_cndmask_b32_e64 v210, v71, v95, s[8:9]
	v_add_f32_e32 v208, v208, v210
	v_add_f32_e32 v209, v209, v211
	s_waitcnt lgkmcnt(1)
	v_mfma_f32_16x16x32_bf16 v[16:19], v[204:207], v[158:161], v[16:19]
	v_mov_b32_e32 v71, v208
	v_mov_b32_e32 v95, v208
	v_mov_b32_e32 v99, v209
	v_mfma_f32_16x16x32_bf16 v[0:3], v[204:207], v[170:173], v[0:3]
	v_mov_b32_e32 v69, v209
	v_permlane32_swap_b32_e32 v71, v95
	s_nop 0
	v_permlane32_swap_b32_e32 v99, v69
	s_waitcnt lgkmcnt(0)
	v_mfma_f32_16x16x32_bf16 v[16:19], v[200:203], v[162:165], v[16:19]
	v_cndmask_b32_e64 v159, v99, v69, s[10:11]
	v_cndmask_b32_e64 v158, v71, v95, s[10:11]
	v_add_f32_e32 v158, v208, v158
	v_add_f32_e32 v159, v209, v159
	v_mfma_f32_16x16x32_bf16 v[0:3], v[200:203], v[166:169], v[0:3]
	v_fma_f32 v114, v114, v156, v158
	v_fma_f32 v115, v115, v157, v159
	v_mov_b32_e32 v71, v73
	v_mov_b32_e32 v69, v75

.Lown_wd3:
	s_waitcnt lgkmcnt(5)
	v_mfma_f32_16x16x32_bf16 v[164:167], v[156:159], v[20:23], 0
	v_cmp_le_u32_e32 vcc, v73, v49
	v_cmp_lt_u32_e64 s[0:1], v73, v49
	v_add_u32_e32 v75, 16, v73
	v_mfma_f32_16x16x32_bf16 v[156:159], v[156:159], v[28:31], 0
	v_add_u32_e32 v139, 2, v73
	v_add_u32_e32 v149, 3, v73
	s_waitcnt lgkmcnt(3)
	v_mfma_f32_16x16x32_bf16 v[216:219], v[168:171], v[20:23], 0
	v_mfma_f32_16x16x32_bf16 v[168:171], v[168:171], v[28:31], 0
	v_mfma_f32_16x16x32_bf16 v[156:159], v[160:163], v[32:35], v[156:159]
	v_mfma_f32_16x16x32_bf16 v[164:167], v[160:163], v[24:27], v[164:167]
	ds_read_b128 v[160:163], v67 offset:6912
	ds_read_b128 v[212:215], v67 offset:6976
	s_nop 4
	v_cndmask_b32_e32 v95, v198, v156, vcc
	v_cmp_gt_u32_e32 vcc, v73, v55
	s_waitcnt lgkmcnt(4)
	v_mfma_f32_16x16x32_bf16 v[168:171], v[200:203], v[32:35], v[168:171]
	v_cndmask_b32_e64 v103, v198, v157, s[0:1]
	v_cmp_lt_u32_e64 s[0:1], v73, v48
	v_cndmask_b32_e32 v99, v164, v198, vcc
	v_mfma_f32_16x16x32_bf16 v[216:219], v[200:203], v[24:27], v[216:219]
	v_cndmask_b32_e64 v105, v198, v165, s[0:1]
	v_cmp_le_u32_e64 s[0:1], v139, v49
	s_nop 1
	v_cndmask_b32_e32 v172, v168, v198, vcc
	s_waitcnt lgkmcnt(3)
	v_mfma_f32_16x16x32_bf16 v[200:203], v[204:207], v[20:23], 0
	v_cmp_le_u32_e32 vcc, v75, v54
	v_add_u32_e32 v168, 17, v73
	v_cndmask_b32_e64 v141, v198, v158, s[0:1]
	v_cmp_le_u32_e64 s[0:1], v139, v48
	v_cndmask_b32_e32 v75, v198, v216, vcc
	v_cmp_le_u32_e32 vcc, v168, v49
	v_cndmask_b32_e64 v139, v198, v166, s[0:1]
	v_cmp_le_u32_e64 s[0:1], v149, v49
	v_cndmask_b32_e32 v173, v198, v169, vcc
	v_cmp_le_u32_e32 vcc, v168, v48
	v_add_u32_e32 v168, 18, v73
	v_cndmask_b32_e64 v153, v198, v159, s[0:1]
	v_cmp_le_u32_e64 s[0:1], v149, v48
	v_cndmask_b32_e32 v178, v198, v217, vcc
	v_cmp_le_u32_e32 vcc, v168, v49
	v_cndmask_b32_e64 v149, v198, v167, s[0:1]
	s_waitcnt lgkmcnt(2)
	v_mfma_f32_16x16x32_bf16 v[164:167], v[208:211], v[24:27], v[200:203]
	v_cndmask_b32_e32 v179, v198, v170, vcc
	v_cmp_le_u32_e32 vcc, v168, v48
	v_add_u32_e32 v168, 19, v73
	v_mfma_f32_16x16x32_bf16 v[156:159], v[204:207], v[28:31], 0
	v_cndmask_b32_e32 v199, v198, v218, vcc
	v_cmp_le_u32_e32 vcc, v168, v49
	v_add_u32_e32 v169, 48, v73
	v_mfma_f32_16x16x32_bf16 v[156:159], v[208:211], v[32:35], v[156:159]
	v_cndmask_b32_e32 v204, v198, v171, vcc
	v_cmp_le_u32_e32 vcc, v168, v48
	v_add_u32_e32 v168, 32, v73
	s_waitcnt lgkmcnt(1)
	v_mfma_f32_16x16x32_bf16 v[200:203], v[160:163], v[20:23], 0
	v_cndmask_b32_e32 v205, v198, v219, vcc
	v_cmp_le_u32_e32 vcc, v168, v48
	v_max3_f32 v209, v95, s5, v103
	v_mfma_f32_16x16x32_bf16 v[160:163], v[160:163], v[28:31], 0
	v_cndmask_b32_e32 v206, v198, v164, vcc
	v_add_u32_e32 v164, 33, v73
	v_cmp_le_u32_e32 vcc, v164, v48
	v_max3_f32 v209, v209, v141, v153
	v_max3_f32 v209, v209, v172, v173
	v_cndmask_b32_e32 v207, v198, v165, vcc
	v_add_u32_e32 v165, 34, v73
	v_cmp_le_u32_e32 vcc, v165, v48
	s_waitcnt lgkmcnt(0)
	v_mfma_f32_16x16x32_bf16 v[160:163], v[212:215], v[32:35], v[160:163]
	v_max3_f32 v209, v209, v179, v204
	v_cndmask_b32_e32 v208, v198, v166, vcc
	v_cmp_le_u32_e32 vcc, v168, v49
	v_add_u32_e32 v166, 35, v73
	v_mfma_f32_16x16x32_bf16 v[200:203], v[212:215], v[24:27], v[200:203]
	v_cndmask_b32_e32 v210, v198, v156, vcc
	v_cmp_le_u32_e32 vcc, v164, v49
	v_add_u32_e32 v170, 49, v73
	v_max3_f32 v137, v99, s5, v105
	v_cndmask_b32_e32 v211, v198, v157, vcc
	v_cmp_le_u32_e32 vcc, v165, v49
	v_max3_f32 v156, v209, v210, v211
	v_max3_f32 v137, v137, v139, v149
	v_cndmask_b32_e32 v209, v198, v158, vcc
	v_cmp_le_u32_e32 vcc, v166, v49
	v_add_u32_e32 v171, 50, v73
	v_max3_f32 v137, v137, v75, v178
	v_cndmask_b32_e32 v212, v198, v159, vcc
	v_cmp_le_u32_e32 vcc, v166, v48
	v_max3_f32 v137, v137, v199, v205
	v_add_u32_e32 v73, 51, v73
	v_cndmask_b32_e32 v213, v198, v167, vcc
	v_cmp_le_u32_e32 vcc, v169, v49
	v_max3_f32 v137, v137, v206, v207
	v_max3_f32 v137, v137, v208, v213
	v_cndmask_b32_e32 v214, v198, v160, vcc
	v_cmp_le_u32_e32 vcc, v169, v48
	v_max3_f32 v156, v156, v209, v212
	s_nop 0
	v_cndmask_b32_e32 v200, v198, v200, vcc
	v_cmp_le_u32_e32 vcc, v170, v49
	s_nop 1
	v_cndmask_b32_e32 v215, v198, v161, vcc
	v_cmp_le_u32_e32 vcc, v170, v48
	v_max3_f32 v156, v156, v214, v215
	s_nop 0
	v_cndmask_b32_e32 v201, v198, v201, vcc
	v_cmp_le_u32_e32 vcc, v171, v49
	v_max3_f32 v137, v137, v200, v201
	s_nop 0
	v_cndmask_b32_e32 v228, v198, v162, vcc
	v_cmp_le_u32_e32 vcc, v171, v48
	s_nop 1
	v_cndmask_b32_e32 v202, v198, v202, vcc
	v_cmp_le_u32_e32 vcc, v73, v49
	s_nop 1
	v_cndmask_b32_e32 v230, v198, v163, vcc
	v_cmp_le_u32_e32 vcc, v73, v48
	v_max3_f32 v156, v156, v228, v230
	s_nop 0
	v_cndmask_b32_e32 v73, v198, v203, vcc
	v_max3_f32 v137, v137, v202, v73
	v_mov_b32_e32 v157, v137
	s_nop 1
	v_permlane16_swap_b32_e32 v157, v137
	v_max_f32_e32 v137, v137, v157
	v_mov_b32_e32 v157, v156
	s_nop 1
	v_permlane16_swap_b32_e32 v157, v156
	v_max_f32_e32 v157, v156, v157
	v_mov_b32_e32 v156, v137
	v_mov_b32_e32 v158, v157
	s_nop 1
	v_permlane32_swap_b32_e32 v156, v137
	v_permlane32_swap_b32_e32 v158, v157
	v_max3_f32 v232, v69, v157, v158
	v_sub_f32_e32 v69, v69, v232
	v_exp_f32_e32 v157, v69
	v_sub_f32_e32 v69, v95, v232
	v_exp_f32_e32 v69, v69
	v_max3_f32 v137, v71, v137, v156
	v_sub_f32_e32 v71, v71, v137
	v_exp_f32_e32 v156, v71
	v_sub_f32_e32 v71, v99, v137
	v_cmp_lt_f32_e32 vcc, s22, v95
	v_exp_f32_e32 v71, v71
	v_pk_mul_f32 v[42:43], v[42:43], v[156:157] op_sel_hi:[1,0]
	v_cndmask_b32_e32 v159, 0, v69, vcc
	v_sub_f32_e32 v69, v103, v232
	v_exp_f32_e32 v69, v69
	v_cmp_lt_f32_e32 vcc, s22, v99
	v_pk_mul_f32 v[40:41], v[40:41], v[156:157] op_sel_hi:[1,0]
	v_add_u32_e32 v95, 0x4000, v65
	v_cndmask_b32_e32 v158, 0, v71, vcc
	v_sub_f32_e32 v71, v105, v137
	v_cmp_lt_f32_e32 vcc, s22, v103
	v_exp_f32_e32 v71, v71
	v_pk_add_f32 v[162:163], v[158:159], 0 op_sel_hi:[1,0]
	v_cndmask_b32_e32 v161, 0, v69, vcc
	v_sub_f32_e32 v69, v141, v232
	v_exp_f32_e32 v69, v69
	v_cmp_lt_f32_e32 vcc, s22, v105
	v_pk_mul_f32 v[46:47], v[46:47], v[156:157] op_sel_hi:[1,0]
	v_pk_mul_f32 v[44:45], v[44:45], v[156:157] op_sel_hi:[1,0]
	v_cndmask_b32_e32 v160, 0, v71, vcc
	v_sub_f32_e32 v71, v139, v137
	v_cmp_lt_f32_e32 vcc, s22, v141
	v_pk_add_f32 v[164:165], v[160:161], v[162:163]
	v_exp_f32_e32 v71, v71
	v_cndmask_b32_e32 v163, 0, v69, vcc
	v_sub_f32_e32 v69, v153, v232
	v_exp_f32_e32 v69, v69
	v_cmp_lt_f32_e32 vcc, s22, v139
	v_pk_mul_f32 v[38:39], v[38:39], v[156:157] op_sel_hi:[1,0]
	v_pk_mul_f32 v[36:37], v[36:37], v[156:157] op_sel_hi:[1,0]
	v_cndmask_b32_e32 v162, 0, v71, vcc
	v_sub_f32_e32 v71, v149, v137
	v_cmp_lt_f32_e32 vcc, s22, v153
	v_pk_add_f32 v[166:167], v[162:163], v[164:165]
	v_exp_f32_e32 v71, v71
	v_cndmask_b32_e32 v165, 0, v69, vcc
	v_sub_f32_e32 v69, v172, v232
	v_exp_f32_e32 v69, v69
	v_cmp_lt_f32_e32 vcc, s22, v149
	v_pk_mul_f32 v[18:19], v[18:19], v[156:157] op_sel_hi:[1,0]
	v_pk_mul_f32 v[16:17], v[16:17], v[156:157] op_sel_hi:[1,0]
	v_cndmask_b32_e32 v164, 0, v71, vcc
	v_sub_f32_e32 v71, v75, v137
	v_cmp_lt_f32_e32 vcc, s22, v172
	v_pk_add_f32 v[168:169], v[164:165], v[166:167]
	v_exp_f32_e32 v71, v71
	v_cndmask_b32_e32 v167, 0, v69, vcc
	v_sub_f32_e32 v69, v173, v232
	v_exp_f32_e32 v69, v69
	v_cmp_lt_f32_e32 vcc, s22, v75
	s_nop 1
	v_cndmask_b32_e32 v166, 0, v71, vcc
	v_sub_f32_e32 v71, v178, v137
	v_cmp_lt_f32_e32 vcc, s22, v173
	v_pk_add_f32 v[170:171], v[166:167], v[168:169]
	v_exp_f32_e32 v71, v71
	v_cndmask_b32_e32 v169, 0, v69, vcc
	v_sub_f32_e32 v69, v179, v232
	v_exp_f32_e32 v69, v69
	v_cmp_lt_f32_e32 vcc, s22, v178
	s_nop 1
	v_cndmask_b32_e32 v168, 0, v71, vcc
	v_sub_f32_e32 v71, v199, v137
	v_cmp_lt_f32_e32 vcc, s22, v179
	v_pk_add_f32 v[172:173], v[168:169], v[170:171]
	v_exp_f32_e32 v71, v71
	v_cndmask_b32_e32 v171, 0, v69, vcc
	v_sub_f32_e32 v69, v204, v232
	v_exp_f32_e32 v69, v69
	v_cmp_lt_f32_e32 vcc, s22, v199
	s_nop 1
	v_cndmask_b32_e32 v170, 0, v71, vcc
	v_sub_f32_e32 v71, v205, v137
	v_cmp_lt_f32_e32 vcc, s22, v204
	v_pk_add_f32 v[178:179], v[170:171], v[172:173]
	v_exp_f32_e32 v71, v71
	v_cndmask_b32_e32 v173, 0, v69, vcc
	v_sub_f32_e32 v69, v206, v137
	v_exp_f32_e32 v69, v69
	v_cmp_lt_f32_e32 vcc, s22, v205
	s_nop 1
	v_cndmask_b32_e32 v172, 0, v71, vcc
	v_sub_f32_e32 v71, v210, v232
	v_cmp_lt_f32_e32 vcc, s22, v206
	v_exp_f32_e32 v71, v71
	v_pk_add_f32 v[178:179], v[172:173], v[178:179]
	v_cndmask_b32_e32 v216, 0, v69, vcc
	v_sub_f32_e32 v69, v211, v232
	v_exp_f32_e32 v69, v69
	v_cmp_lt_f32_e32 vcc, s22, v210
	v_cvt_pk_bf16_f32 v203, v170, v172
	s_nop 0
	v_cndmask_b32_e32 v217, 0, v71, vcc
	v_sub_f32_e32 v71, v207, v137
	v_cmp_lt_f32_e32 vcc, s22, v211
	v_exp_f32_e32 v71, v71
	v_pk_add_f32 v[178:179], v[216:217], v[178:179]
	v_cndmask_b32_e32 v219, 0, v69, vcc
	v_sub_f32_e32 v69, v209, v232
	v_exp_f32_e32 v69, v69
	v_cmp_lt_f32_e32 vcc, s22, v207
	s_nop 1
	v_cndmask_b32_e32 v218, 0, v71, vcc
	v_sub_f32_e32 v71, v208, v137
	v_cmp_lt_f32_e32 vcc, s22, v209
	v_exp_f32_e32 v71, v71
	v_cvt_pk_bf16_f32 v204, v216, v218
	v_cndmask_b32_e32 v221, 0, v69, vcc
	v_sub_f32_e32 v69, v212, v232
	v_exp_f32_e32 v69, v69
	v_cmp_lt_f32_e32 vcc, s22, v208
	v_mov_b32_e32 v216, v157
	v_pk_add_f32 v[178:179], v[218:219], v[178:179]
	v_cndmask_b32_e32 v220, 0, v71, vcc
	v_sub_f32_e32 v71, v213, v137
	v_cmp_lt_f32_e32 vcc, s22, v212
	v_exp_f32_e32 v71, v71
	ds_read2_b64 v[208:211], v65 offset1:4
	v_cndmask_b32_e32 v223, 0, v69, vcc
	v_sub_f32_e32 v69, v214, v232
	v_exp_f32_e32 v69, v69
	v_cmp_lt_f32_e32 vcc, s22, v213
	v_pk_mul_f32 v[10:11], v[10:11], v[216:217] op_sel_hi:[1,0]
	v_pk_mul_f32 v[8:9], v[8:9], v[216:217] op_sel_hi:[1,0]
	v_cndmask_b32_e32 v222, 0, v71, vcc
	v_sub_f32_e32 v71, v200, v137
	v_cmp_lt_f32_e32 vcc, s22, v214
	v_exp_f32_e32 v71, v71
	v_pk_add_f32 v[178:179], v[220:221], v[178:179]
	v_cndmask_b32_e32 v225, 0, v69, vcc
	v_sub_f32_e32 v69, v215, v232
	v_exp_f32_e32 v69, v69
	v_cmp_lt_f32_e32 vcc, s22, v200
	v_cvt_pk_bf16_f32 v200, v158, v160
	v_cvt_pk_bf16_f32 v160, v167, v169
	v_cndmask_b32_e32 v224, 0, v71, vcc
	v_sub_f32_e32 v71, v201, v137
	v_cmp_lt_f32_e32 vcc, s22, v215
	v_exp_f32_e32 v71, v71
	v_cvt_pk_bf16_f32 v158, v159, v161
	v_cndmask_b32_e32 v227, 0, v69, vcc
	v_sub_f32_e32 v69, v228, v232
	v_exp_f32_e32 v69, v69
	v_cmp_lt_f32_e32 vcc, s22, v201
	v_cvt_pk_bf16_f32 v161, v171, v173
	v_cvt_pk_bf16_f32 v201, v162, v164
	v_cndmask_b32_e32 v226, 0, v71, vcc
	v_sub_f32_e32 v71, v202, v137
	v_cmp_lt_f32_e32 vcc, s22, v228
	v_exp_f32_e32 v71, v71
	v_cvt_pk_bf16_f32 v159, v163, v165
	v_cndmask_b32_e32 v229, 0, v69, vcc
	v_sub_f32_e32 v69, v230, v232
	v_exp_f32_e32 v69, v69
	v_cmp_lt_f32_e32 vcc, s22, v202
	v_cvt_pk_bf16_f32 v202, v166, v168
	v_pk_add_f32 v[178:179], v[222:223], v[178:179]
	v_cndmask_b32_e32 v228, 0, v71, vcc
	v_cmp_lt_f32_e32 vcc, s22, v230
	v_sub_f32_e32 v71, v73, v137
	v_exp_f32_e32 v71, v71
	v_cndmask_b32_e32 v231, 0, v69, vcc
	v_cmp_lt_f32_e32 vcc, s22, v73
	v_add_u32_e32 v73, 0x2000, v65
	ds_read2_b64 v[166:169], v73 offset0:32 offset1:36
	ds_read2_b64 v[170:173], v73 offset0:40 offset1:44
	s_waitcnt lgkmcnt(1)
	v_mfma_f32_16x16x32_bf16 v[40:43], v[166:169], v[200:203], v[40:43]
	v_add_f32_e64 v178, v224, v178
	v_add_f32_e64 v179, v225, v179
	v_cndmask_b32_e32 v230, 0, v71, vcc
	v_add_f32_e32 v178, v226, v178
	v_add_f32_e32 v179, v227, v179
	v_mfma_f32_16x16x32_bf16 v[8:11], v[166:169], v[158:161], v[8:11]
	ds_read2_b64 v[166:169], v95 offset0:64 offset1:68
	v_cvt_pk_bf16_f32 v205, v220, v222
	v_cvt_pk_bf16_f32 v206, v224, v226
	v_cvt_pk_bf16_f32 v207, v228, v230
	v_cvt_pk_bf16_f32 v162, v217, v219
	v_cvt_pk_bf16_f32 v163, v221, v223
	v_cvt_pk_bf16_f32 v164, v225, v227
	v_cvt_pk_bf16_f32 v165, v229, v231
	v_add_f32_e32 v178, v228, v178
	v_add_f32_e32 v179, v229, v179
	s_waitcnt lgkmcnt(1)
	v_mfma_f32_16x16x32_bf16 v[40:43], v[170:173], v[204:207], v[40:43]
	v_add_f32_e64 v178, v230, v178
	v_add_f32_e64 v179, v231, v179
	v_mul_f32_e32 v14, v14, v216
	v_mul_f32_e32 v15, v15, v216
	v_mov_b32_e32 v75, v179
	v_mfma_f32_16x16x32_bf16 v[8:11], v[170:173], v[162:165], v[8:11]
	ds_read2_b64 v[170:173], v95 offset0:72 offset1:76
	v_mov_b32_e32 v73, v179
	v_mul_f32_e32 v12, v12, v216
	v_mul_f32_e32 v13, v13, v216
	s_nop 0
	v_permlane16_swap_b32_e32 v75, v73
	v_mfma_f32_16x16x32_bf16 v[44:47], v[208:211], v[200:203], v[44:47]
	v_mul_f32_e64 v6, v6, v216
	v_mul_f32_e64 v7, v7, v216
	v_mul_f32_e32 v4, v4, v216
	v_mul_f32_e32 v5, v5, v216
	ds_read2_b64 v[212:215], v65 offset0:8 offset1:12
	v_mfma_f32_16x16x32_bf16 v[12:15], v[208:211], v[158:161], v[12:15]
	v_cndmask_b32_e64 v209, v75, v73, s[8:9]
	v_add_u32_e32 v73, 0x6000, v65
	v_mov_b32_e32 v69, v178
	s_waitcnt lgkmcnt(2)
	v_mfma_f32_16x16x32_bf16 v[36:39], v[166:169], v[200:203], v[36:39]
	v_mov_b32_e32 v71, v178
	v_mul_f32_e32 v2, v2, v216
	v_mul_f32_e32 v3, v3, v216
	v_mul_f32_e32 v0, v0, v216
	v_mul_f32_e32 v1, v1, v216
	v_mfma_f32_16x16x32_bf16 v[4:7], v[166:169], v[158:161], v[4:7]
	ds_read2_b64 v[166:169], v73 offset0:96 offset1:100
	v_permlane16_swap_b32_e32 v69, v71
	s_waitcnt lgkmcnt(2)
	v_mfma_f32_16x16x32_bf16 v[36:39], v[170:173], v[204:207], v[36:39]
	v_cndmask_b32_e64 v208, v69, v71, s[8:9]
	v_add_f32_e32 v178, v178, v208
	v_add_f32_e32 v179, v179, v209
	v_mfma_f32_16x16x32_bf16 v[4:7], v[170:173], v[162:165], v[4:7]
	ds_read2_b64 v[170:173], v73 offset0:104 offset1:108
	v_mov_b32_e32 v69, v178
	v_mov_b32_e32 v71, v178
	s_waitcnt lgkmcnt(1)
	v_mfma_f32_16x16x32_bf16 v[16:19], v[166:169], v[200:203], v[16:19]
	v_mov_b32_e32 v75, v179
	v_mov_b32_e32 v73, v179
	v_permlane32_swap_b32_e32 v69, v71
	v_mfma_f32_16x16x32_bf16 v[0:3], v[166:169], v[158:161], v[0:3]
	v_permlane32_swap_b32_e32 v75, v73
	v_cndmask_b32_e64 v159, v75, v73, s[10:11]
	v_mfma_f32_16x16x32_bf16 v[44:47], v[212:215], v[204:207], v[44:47]
	v_cndmask_b32_e64 v158, v69, v71, s[10:11]
	v_add_f32_e32 v158, v178, v158
	v_add_f32_e32 v159, v179, v159
	v_mov_b32_e32 v71, v137
	v_mfma_f32_16x16x32_bf16 v[12:15], v[212:215], v[162:165], v[12:15]
	v_fma_f32 v114, v114, v156, v158
	v_fma_f32 v115, v115, v157, v159
	v_mov_b32_e32 v69, v232
	s_waitcnt lgkmcnt(0)
	v_mfma_f32_16x16x32_bf16 v[16:19], v[170:173], v[204:207], v[16:19]
	v_mfma_f32_16x16x32_bf16 v[0:3], v[170:173], v[162:165], v[0:3]
	s_branch .LBB0_291

.LBB0_416:
	v_cvt_pk_bf16_f32 v56, v28, v29
	v_cvt_pk_bf16_f32 v57, v30, v31
	v_cvt_pk_bf16_f32 v58, v32, v33
	v_cvt_pk_bf16_f32 v59, v34, v35
	ds_read_b128 v[28:31], v128 offset:35840
	ds_read_b128 v[36:39], v128 offset:40192
	ds_read_b128 v[32:35], v128 offset:53248
	ds_read_b128 v[40:43], v128 offset:57600
	ds_read_b128 v[44:47], v128 offset:44544
	ds_read_b128 v[48:51], v128 offset:61952
	ds_read_b128 v[52:55], v128 offset:48896
	ds_read_b128 v[60:63], v129 offset:13056
	ds_read_b128 v[64:67], v130
	ds_read_b128 v[68:71], v130 offset:16
	ds_read_b128 v[72:75], v131
	ds_read_b128 v[212:215], v131 offset:16
	ds_read_b128 v[216:219], v200 offset:64
	ds_read_b128 v[220:223], v200 offset:336
	ds_read_b128 v[224:227], v131 offset:512
	ds_read_b128 v[228:231], v131 offset:528
	ds_read_b128 v[232:235], v131 offset:1024
	ds_read_b128 v[236:239], v131 offset:1040
	s_waitcnt lgkmcnt(14)
	v_mfma_f32_16x16x32_bf16 v[28:31], v[56:59], v[28:31], 0
	s_and_b64 vcc, exec, s[40:41]
	s_waitcnt lgkmcnt(5)
	v_and_b32_e32 v113, 0xffff0000, v216
	v_lshlrev_b32_e32 v112, 16, v216
	v_mfma_f32_16x16x32_bf16 v[32:35], v[56:59], v[32:35], 0
	v_fma_f32 v64, v72, v112, v64
	v_fma_f32 v65, v73, v113, v65
	s_waitcnt lgkmcnt(4)
	v_and_b32_e32 v73, 0xffff0000, v220
	v_lshlrev_b32_e32 v72, 16, v220
	v_mfma_f32_16x16x32_bf16 v[36:39], v[56:59], v[36:39], 0
	s_waitcnt lgkmcnt(3)
	v_fma_f32 v64, v224, v72, v64
	v_fma_f32 v65, v225, v73, v65
	v_mfma_f32_16x16x32_bf16 v[40:43], v[56:59], v[40:43], 0
	v_mfma_f32_16x16x32_bf16 v[44:47], v[56:59], v[44:47], 0
	v_mfma_f32_16x16x32_bf16 v[48:51], v[56:59], v[48:51], 0
	v_mfma_f32_16x16x32_bf16 v[52:55], v[56:59], v[52:55], 0
	v_mfma_f32_16x16x32_bf16 v[60:63], v[56:59], v[60:63], 0
	ds_read_b128 v[240:243], v200 offset:608
	ds_read_b128 v[244:247], v200 offset:880
	ds_read_b128 v[56:59], v131 offset:1536
	ds_read_b128 v[248:251], v131 offset:1552
	s_waitcnt lgkmcnt(3)
	v_and_b32_e32 v73, 0xffff0000, v240
	v_lshlrev_b32_e32 v72, 16, v240
	v_fma_f32 v64, v232, v72, v64
	v_fma_f32 v65, v233, v73, v65
	s_waitcnt lgkmcnt(2)
	v_and_b32_e32 v73, 0xffff0000, v244
	v_lshlrev_b32_e32 v72, 16, v244
	s_waitcnt lgkmcnt(1)
	v_pk_fma_f32 v[56:57], v[56:57], v[72:73], v[64:65]
	v_and_b32_e32 v65, 0xffff0000, v218
	v_lshlrev_b32_e32 v64, 16, v218
	v_pk_fma_f32 v[64:65], v[212:213], v[64:65], v[68:69]
	v_and_b32_e32 v69, 0xffff0000, v222
	v_lshlrev_b32_e32 v68, 16, v222
	v_pk_fma_f32 v[64:65], v[228:229], v[68:69], v[64:65]
	v_and_b32_e32 v69, 0xffff0000, v242
	v_lshlrev_b32_e32 v68, 16, v242
	v_pk_fma_f32 v[64:65], v[236:237], v[68:69], v[64:65]
	v_and_b32_e32 v69, 0xffff0000, v246
	v_lshlrev_b32_e32 v68, 16, v246
	s_waitcnt lgkmcnt(0)
	v_pk_fma_f32 v[64:65], v[248:249], v[68:69], v[64:65]
	v_and_b32_e32 v69, 0xffff0000, v217
	v_lshlrev_b32_e32 v68, 16, v217
	v_pk_fma_f32 v[66:67], v[74:75], v[68:69], v[66:67]
	v_and_b32_e32 v69, 0xffff0000, v221
	v_lshlrev_b32_e32 v68, 16, v221
	v_pk_fma_f32 v[66:67], v[226:227], v[68:69], v[66:67]
	v_and_b32_e32 v69, 0xffff0000, v241
	v_lshlrev_b32_e32 v68, 16, v241
	v_pk_fma_f32 v[66:67], v[234:235], v[68:69], v[66:67]
	v_and_b32_e32 v69, 0xffff0000, v245
	v_lshlrev_b32_e32 v68, 16, v245
	v_pk_fma_f32 v[58:59], v[58:59], v[68:69], v[66:67]
	v_and_b32_e32 v67, 0xffff0000, v219
	v_lshlrev_b32_e32 v66, 16, v219
	v_pk_fma_f32 v[66:67], v[214:215], v[66:67], v[70:71]
	v_and_b32_e32 v69, 0xffff0000, v223
	v_lshlrev_b32_e32 v68, 16, v223
	v_pk_fma_f32 v[66:67], v[230:231], v[68:69], v[66:67]
	v_and_b32_e32 v69, 0xffff0000, v243
	v_lshlrev_b32_e32 v68, 16, v243
	v_pk_fma_f32 v[66:67], v[238:239], v[68:69], v[66:67]
	v_and_b32_e32 v69, 0xffff0000, v247
	v_lshlrev_b32_e32 v68, 16, v247
	v_pk_fma_f32 v[66:67], v[250:251], v[68:69], v[66:67]
	s_cbranch_vccnz .LBB0_418
	ds_write_b128 v125, v[56:59] offset:128
	ds_write_b128 v125, v[64:67] offset:144
.LBB0_418:
	v_cvt_pk_bf16_f32 v68, v56, v57
	v_cvt_pk_bf16_f32 v69, v58, v59
	v_cvt_pk_bf16_f32 v70, v64, v65
	v_cvt_pk_bf16_f32 v71, v66, v67
	ds_read_b128 v[56:59], v128 offset:35904
	ds_read_b128 v[64:67], v128 offset:40256
	s_waitcnt lgkmcnt(1)
	v_mfma_f32_16x16x32_bf16 v[28:31], v[68:71], v[56:59], v[28:31]
	ds_read_b128 v[56:59], v128 offset:53312
	ds_read_b128 v[72:75], v128 offset:57664
	s_andn2_b64 vcc, exec, s[60:61]
	s_waitcnt lgkmcnt(1)
	v_mfma_f32_16x16x32_bf16 v[32:35], v[68:71], v[56:59], v[32:35]
	v_mfma_f32_16x16x32_bf16 v[36:39], v[68:71], v[64:67], v[36:39]
	s_waitcnt lgkmcnt(0)
	v_mfma_f32_16x16x32_bf16 v[40:43], v[68:71], v[72:75], v[40:43]
	ds_read_b128 v[56:59], v128 offset:44608
	ds_read_b128 v[64:67], v128 offset:62016
	ds_read_b128 v[72:75], v128 offset:48960
	ds_read_b128 v[212:215], v132 offset:13056
	ds_read_b128 v[216:219], v133
	ds_read_b128 v[220:223], v133 offset:16
	s_waitcnt lgkmcnt(4)
	v_mfma_f32_16x16x32_bf16 v[48:51], v[68:71], v[64:67], v[48:51]
	ds_read_b128 v[64:67], v134
	ds_read_b128 v[224:227], v134 offset:16
	ds_read_b128 v[228:231], v200 offset:128
	ds_read_b128 v[232:235], v200 offset:400
	s_waitcnt lgkmcnt(1)
	v_and_b32_e32 v113, 0xffff0000, v228
	v_mfma_f32_16x16x32_bf16 v[44:47], v[68:71], v[56:59], v[44:47]
	v_lshlrev_b32_e32 v112, 16, v228
	v_fma_f32 v64, v64, v112, v216
	v_fma_f32 v65, v65, v113, v217
	s_waitcnt lgkmcnt(0)
	v_and_b32_e32 v113, 0xffff0000, v232
	v_mfma_f32_16x16x32_bf16 v[56:59], v[68:71], v[72:75], v[52:55]
	s_nop 2
	ds_read_b128 v[52:55], v134 offset:512
	ds_read_b128 v[72:75], v134 offset:528
	ds_read_b128 v[236:239], v134 offset:1024
	ds_read_b128 v[240:243], v134 offset:1040
	v_lshlrev_b32_e32 v112, 16, v232
	s_waitcnt lgkmcnt(3)
	v_fma_f32 v52, v52, v112, v64
	v_fma_f32 v53, v53, v113, v65
	v_mfma_f32_16x16x32_bf16 v[60:63], v[68:71], v[212:215], v[60:63]
	ds_read_b128 v[68:71], v200 offset:672
	ds_read_b128 v[212:215], v200 offset:944
	ds_read_b128 v[244:247], v134 offset:1536
	ds_read_b128 v[248:251], v134 offset:1552
	v_and_b32_e32 v113, 0xffff0000, v234
	s_waitcnt lgkmcnt(3)
	v_and_b32_e32 v65, 0xffff0000, v68
	v_lshlrev_b32_e32 v64, 16, v68
	v_pk_fma_f32 v[52:53], v[236:237], v[64:65], v[52:53]
	s_waitcnt lgkmcnt(2)
	v_and_b32_e32 v65, 0xffff0000, v212
	v_lshlrev_b32_e32 v64, 16, v212
	s_waitcnt lgkmcnt(1)
	v_pk_fma_f32 v[52:53], v[244:245], v[64:65], v[52:53]
	v_and_b32_e32 v65, 0xffff0000, v230
	v_lshlrev_b32_e32 v64, 16, v230
	v_pk_fma_f32 v[64:65], v[224:225], v[64:65], v[220:221]
	v_lshlrev_b32_e32 v112, 16, v234
	v_pk_fma_f32 v[64:65], v[72:73], v[112:113], v[64:65]
	v_and_b32_e32 v73, 0xffff0000, v70
	v_lshlrev_b32_e32 v72, 16, v70
	v_pk_fma_f32 v[64:65], v[240:241], v[72:73], v[64:65]
	v_and_b32_e32 v73, 0xffff0000, v214
	v_lshlrev_b32_e32 v72, 16, v214
	s_waitcnt lgkmcnt(0)
	v_pk_fma_f32 v[64:65], v[248:249], v[72:73], v[64:65]
	v_and_b32_e32 v73, 0xffff0000, v229
	v_lshlrev_b32_e32 v72, 16, v229
	v_pk_fma_f32 v[66:67], v[66:67], v[72:73], v[218:219]
	v_and_b32_e32 v73, 0xffff0000, v233
	v_lshlrev_b32_e32 v72, 16, v233
	v_pk_fma_f32 v[54:55], v[54:55], v[72:73], v[66:67]
	v_and_b32_e32 v67, 0xffff0000, v69
	v_lshlrev_b32_e32 v66, 16, v69
	v_pk_fma_f32 v[54:55], v[238:239], v[66:67], v[54:55]
	v_and_b32_e32 v67, 0xffff0000, v213
	v_lshlrev_b32_e32 v66, 16, v213
	v_pk_fma_f32 v[54:55], v[246:247], v[66:67], v[54:55]
	v_and_b32_e32 v67, 0xffff0000, v231
	v_lshlrev_b32_e32 v66, 16, v231
	v_pk_fma_f32 v[66:67], v[226:227], v[66:67], v[222:223]
	v_and_b32_e32 v69, 0xffff0000, v235
	v_lshlrev_b32_e32 v68, 16, v235
	v_pk_fma_f32 v[66:67], v[74:75], v[68:69], v[66:67]
	v_and_b32_e32 v69, 0xffff0000, v71
	v_lshlrev_b32_e32 v68, 16, v71
	v_pk_fma_f32 v[66:67], v[242:243], v[68:69], v[66:67]
	v_and_b32_e32 v69, 0xffff0000, v215
	v_lshlrev_b32_e32 v68, 16, v215
	v_cndmask_b32_e64 v70, 0, 1, s[60:61]
	v_cmp_ne_u32_e64 s[40:41], 1, v70
	v_pk_fma_f32 v[66:67], v[250:251], v[68:69], v[66:67]
	s_cbranch_vccnz .LBB0_420
	ds_write_b128 v125, v[52:55]
	ds_write_b128 v125, v[64:67] offset:16
.LBB0_420:
	v_cvt_pk_bf16_f32 v212, v52, v53
	v_cvt_pk_bf16_f32 v213, v54, v55
	v_cvt_pk_bf16_f32 v214, v64, v65
	v_cvt_pk_bf16_f32 v215, v66, v67
	ds_read_b128 v[52:55], v128 offset:35968
	ds_read_b128 v[72:75], v128 offset:40320
	s_waitcnt lgkmcnt(1)
	v_mfma_f32_16x16x32_bf16 v[64:67], v[212:215], v[52:55], v[28:31]
	s_nop 2
	ds_read_b128 v[28:31], v128 offset:53376
	ds_read_b128 v[52:55], v128 offset:57728
	s_and_b64 vcc, exec, s[40:41]
	s_waitcnt lgkmcnt(1)
	v_mfma_f32_16x16x32_bf16 v[68:71], v[212:215], v[28:31], v[32:35]
	ds_read_b128 v[28:31], v128 offset:44672
	s_nop 1
	ds_read_b128 v[32:35], v128 offset:62080
	ds_read_b128 v[216:219], v128 offset:49024
	v_mfma_f32_16x16x32_bf16 v[72:75], v[212:215], v[72:75], v[36:39]
	s_waitcnt lgkmcnt(3)
	v_mfma_f32_16x16x32_bf16 v[36:39], v[212:215], v[52:55], v[40:43]
	s_waitcnt lgkmcnt(2)
	v_mfma_f32_16x16x32_bf16 v[52:55], v[212:215], v[28:31], v[44:47]
	s_nop 2
	ds_read_b128 v[44:47], v135 offset:13056
	ds_read_b128 v[220:223], v136
	ds_read_b128 v[224:227], v136 offset:16
	s_waitcnt lgkmcnt(4)
	v_mfma_f32_16x16x32_bf16 v[40:43], v[212:215], v[32:35], v[48:51]
	s_nop 2
	ds_read_b128 v[48:51], v137
	ds_read_b128 v[228:231], v137 offset:16
	ds_read_b128 v[232:235], v200 offset:192
	ds_read_b128 v[236:239], v200 offset:464
	s_waitcnt lgkmcnt(1)
	v_and_b32_e32 v113, 0xffff0000, v232
	v_mfma_f32_16x16x32_bf16 v[28:31], v[212:215], v[216:219], v[56:59]
	s_nop 2
	ds_read_b128 v[56:59], v137 offset:512
	ds_read_b128 v[216:219], v137 offset:528
	ds_read_b128 v[240:243], v137 offset:1024
	ds_read_b128 v[244:247], v137 offset:1040
	v_lshlrev_b32_e32 v112, 16, v232
	v_fma_f32 v48, v48, v112, v220
	v_fma_f32 v49, v49, v113, v221
	v_mfma_f32_16x16x32_bf16 v[32:35], v[212:215], v[44:47], v[60:63]
	s_nop 2
	ds_read_b128 v[60:63], v200 offset:736
	ds_read_b128 v[212:215], v200 offset:1008
	ds_read_b128 v[44:47], v137 offset:1536
	ds_read_b128 v[248:251], v137 offset:1552
	s_waitcnt lgkmcnt(8)
	v_and_b32_e32 v113, 0xffff0000, v236
	v_lshlrev_b32_e32 v112, 16, v236
	s_waitcnt lgkmcnt(7)
	v_pk_fma_f32 v[48:49], v[56:57], v[112:113], v[48:49]
	s_waitcnt lgkmcnt(3)
	v_and_b32_e32 v57, 0xffff0000, v60
	v_lshlrev_b32_e32 v56, 16, v60
	v_pk_fma_f32 v[48:49], v[240:241], v[56:57], v[48:49]
	s_waitcnt lgkmcnt(2)
	v_and_b32_e32 v57, 0xffff0000, v212
	v_lshlrev_b32_e32 v56, 16, v212
	s_waitcnt lgkmcnt(1)
	v_pk_fma_f32 v[44:45], v[44:45], v[56:57], v[48:49]
	v_and_b32_e32 v49, 0xffff0000, v234
	v_lshlrev_b32_e32 v48, 16, v234
	v_pk_fma_f32 v[48:49], v[228:229], v[48:49], v[224:225]
	v_and_b32_e32 v57, 0xffff0000, v238
	v_lshlrev_b32_e32 v56, 16, v238
	v_pk_fma_f32 v[48:49], v[216:217], v[56:57], v[48:49]
	v_and_b32_e32 v57, 0xffff0000, v62
	v_lshlrev_b32_e32 v56, 16, v62
	v_pk_fma_f32 v[48:49], v[244:245], v[56:57], v[48:49]
	v_and_b32_e32 v57, 0xffff0000, v214
	v_lshlrev_b32_e32 v56, 16, v214
	s_waitcnt lgkmcnt(0)
	v_pk_fma_f32 v[48:49], v[248:249], v[56:57], v[48:49]
	v_and_b32_e32 v57, 0xffff0000, v233
	v_lshlrev_b32_e32 v56, 16, v233
	v_pk_fma_f32 v[50:51], v[50:51], v[56:57], v[222:223]
	v_and_b32_e32 v57, 0xffff0000, v237
	v_lshlrev_b32_e32 v56, 16, v237
	v_pk_fma_f32 v[50:51], v[58:59], v[56:57], v[50:51]
	v_and_b32_e32 v57, 0xffff0000, v61
	v_lshlrev_b32_e32 v56, 16, v61
	v_pk_fma_f32 v[50:51], v[242:243], v[56:57], v[50:51]
	v_and_b32_e32 v57, 0xffff0000, v213
	v_lshlrev_b32_e32 v56, 16, v213
	v_pk_fma_f32 v[46:47], v[46:47], v[56:57], v[50:51]
	v_and_b32_e32 v51, 0xffff0000, v235
	v_lshlrev_b32_e32 v50, 16, v235
	v_pk_fma_f32 v[50:51], v[230:231], v[50:51], v[226:227]
	v_and_b32_e32 v57, 0xffff0000, v239
	v_lshlrev_b32_e32 v56, 16, v239
	v_pk_fma_f32 v[50:51], v[218:219], v[56:57], v[50:51]
	v_and_b32_e32 v57, 0xffff0000, v63
	v_lshlrev_b32_e32 v56, 16, v63
	v_pk_fma_f32 v[50:51], v[246:247], v[56:57], v[50:51]
	v_and_b32_e32 v57, 0xffff0000, v215
	v_lshlrev_b32_e32 v56, 16, v215
	v_pk_fma_f32 v[50:51], v[250:251], v[56:57], v[50:51]
	s_cbranch_vccnz .LBB0_422
	ds_write_b128 v125, v[44:47] offset:128
	ds_write_b128 v125, v[48:51] offset:144
